# select_row: packed digit phases for all four key bytes (single ordinary probes only at bits 31, 23, 15, 7); same threshold
# baseline (speedup 1.0000x reference)
; DI void select_row(const float* SC, unsigned* dmask, int b, int t, int lane) {
;     ...
;     if (!hit) {
;     ...
;             const unsigned cand = T | (1u << bit); int cnt; SEL_COUNT(cand, cnt);
;             if (cnt >= 256) { T = cand; if (cnt == 256) { hit = true; break; } }
;         }
;     }
.Ls7_rej:
	s_add_i32 s57, s57, -1
	s_cmp_ge_i32 s57, 0
	s_cbranch_scc1 .Ls7_loop
	s_lshl_b32 s56, s56, s84
	s_or_b32 s14, s14, s56
	s_cmp_eq_u32 s84, 0
	s_cbranch_scc1 .Ls7_fin
	s_add_i32 s84, s84, -1
	s_mov_b32 s80, s84
	s_branch .LBB0_571
.Ls7_fin:
	v_mov_b32_e32 v2, s14
	s_mov_b64 s[8:9], 0
	s_branch .LBB0_582
